# phase 1 static weight-conversion jobs use the real grid size (loaded once); phase 0 transposes loop: grid size / remainder loaded once before the loop instead of per job
# baseline (speedup 1.0000x reference)
.LBB0_452:
	s_mov_b32 s98, 0
	s_load_dword s99, s[54:55], 0x0
	s_waitcnt lgkmcnt(0)
	v_add_u32_e32 v5, 0x100, v200
	v_lshlrev_b32_e32 v0, 2, v200
	v_ashrrev_i32_e32 v3, 3, v200
	v_ashrrev_i32_e32 v5, 3, v5
	v_and_b32_e32 v22, 60, v0
	v_ashrrev_i32_e32 v23, 4, v200
	v_and_b32_e32 v25, 63, v200
	v_and_b32_e32 v16, -8, v3
	v_or_b32_e32 v3, 7, v3
	v_and_b32_e32 v18, -8, v5
	v_or_b32_e32 v5, 7, v5
	v_lshl_add_u32 v0, v22, 2, 0
	v_mul_lo_u32 v1, v23, s48
	v_lshl_add_u32 v2, v25, 2, 0
	v_mul_lo_u32 v4, v16, s48
	v_mul_lo_u32 v3, v3, s48
	v_mul_lo_u32 v6, v18, s48
	v_mul_lo_u32 v5, v5, s48
	v_cmp_eq_u32_e64 s[4:5], 0, v200
	v_cmp_gt_u32_e64 s[6:7], 32, v22
	v_add_u32_e32 v24, 0xae0, v22
	v_ashrrev_i32_e32 v17, 31, v16
	v_ashrrev_i32_e32 v19, 31, v18
	v_add_u32_e32 v26, v0, v1
	v_add_u32_e32 v27, v2, v4
	v_add_u32_e32 v28, v2, v3
	v_add_u32_e32 v29, v2, v6
	v_add_u32_e32 v30, v2, v5
	s_branch .LBB0_455

.LBB0_455:
	v_readlane_b32 s0, v251, 5
	s_lshr_b32 s0, s0, 2
	s_mul_i32 s2, s98, s99
	s_add_i32 s2, s2, s0
	s_add_i32 s98, s98, 1
	v_mov_b32_e32 v0, s2
	s_movk_i32 s0, 0x580
	s_mov_b64 s[12:13], -1
	v_cmp_gt_i32_e32 vcc, s0, v0
	s_movk_i32 s0, 0x57f
	v_readfirstlane_b32 s2, v0
	v_cmp_lt_i32_e64 s[8:9], s0, v0
	s_cbranch_vccnz .LBB0_465
	s_add_i32 s1, s2, 0xfffffa80
	s_cmpk_lt_u32 s1, 0x2c0
	s_cbranch_scc1 .LBB0_466
	s_add_i32 s1, s2, 0xfffff7c0
	s_cmpk_lt_u32 s1, 0x100
	s_cbranch_scc1 .LBB0_467
	s_add_i32 s1, s2, 0xfffff6c0
	s_cmpk_lt_u32 s1, 0x80
	s_cbranch_scc1 .LBB0_468
	s_add_i32 s1, s2, 0xfffff640
	s_cmpk_lt_u32 s1, 0x80
	s_cbranch_scc1 .LBB0_469
	s_cmpk_lt_u32 s1, 0x180
	s_cselect_b64 s[16:17], -1, 0
	s_and_b64 s[10:11], s[16:17], exec
	s_movk_i32 s0, 0xfe80
	s_cselect_b32 s0, 0xffffff80, s0
	v_readlane_b32 s14, v251, 13
	v_readlane_b32 s18, v251, 40
	s_add_i32 s1, s0, s1
	s_movk_i32 s0, 0x400
	v_readlane_b32 s15, v251, 14
	v_readlane_b32 s19, v251, 41
	s_branch .LBB0_470

.LBB0_484:
	s_or_b64 exec, exec, s[4:5]
	v_add_u32_e32 v5, 0x100, v200
	v_lshlrev_b32_e32 v0, 2, v200
	v_ashrrev_i32_e32 v3, 3, v200
	v_ashrrev_i32_e32 v5, 3, v5
	v_and_b32_e32 v22, 60, v0
	v_ashrrev_i32_e32 v23, 4, v200
	v_and_b32_e32 v48, 63, v200
	v_and_b32_e32 v16, -8, v3
	v_or_b32_e32 v3, 7, v3
	v_and_b32_e32 v18, -8, v5
	v_or_b32_e32 v5, 7, v5
	v_lshl_add_u32 v0, v22, 2, 0
	v_mul_lo_u32 v1, v23, s48
	v_lshl_add_u32 v2, v48, 2, 0
	v_mul_lo_u32 v4, v16, s48
	v_mul_lo_u32 v3, v3, s48
	v_mul_lo_u32 v6, v18, s48
	v_mul_lo_u32 v5, v5, s48
	v_ashrrev_i32_e32 v17, 31, v16
	v_ashrrev_i32_e32 v19, 31, v18
	v_add_u32_e32 v24, v0, v1
	v_add_u32_e32 v25, v2, v4
	v_add_u32_e32 v26, v2, v3
	v_add_u32_e32 v27, v2, v6
	v_add_u32_e32 v28, v2, v5
	v_readlane_b32 s0, v249, 7
	v_readlane_b32 s1, v249, 8
	s_load_dword s44, s[54:55], 0x10
	s_load_dword s45, s[54:55], 0x0
	s_waitcnt lgkmcnt(0)
	s_branch .LBB0_487
.LBB0_485:
	s_or_b64 exec, exec, s[8:9]
	s_waitcnt vmcnt(0)
	ds_write_b128 v24, v[4:7]
	ds_write_b128 v24, v[0:3] offset:4352
	ds_write_b128 v24, v[12:15] offset:8704
	ds_write_b128 v24, v[8:11] offset:13056
	v_or_b32_e32 v0, s2, v48
	v_mad_i64_i32 v[0:1], s[4:5], v0, s1, 0
	v_lshl_add_u64 v[0:1], v[0:1], 1, s[6:7]
	s_ashr_i32 s11, s10, 31
	v_add_u32_e32 v6, 0x400, v25
	s_waitcnt lgkmcnt(0)
	s_barrier
	v_lshl_add_u64 v[4:5], s[10:11], 1, v[0:1]
	ds_read2_b32 v[0:1], v25 offset1:68
	ds_read2_b32 v[2:3], v25 offset0:136 offset1:204
	ds_read2_b32 v[6:7], v6 offset0:16 offset1:84
	ds_read_b32 v8, v25 offset:1632
	ds_read_b32 v9, v26
	v_add_u32_e32 v10, 0x400, v27
	ds_read_b32 v14, v27 offset:1632
	ds_read_b32 v15, v28
	s_waitcnt lgkmcnt(6)
	v_cvt_pk_bf16_f32 v0, v0, v1
	s_waitcnt lgkmcnt(5)
	v_cvt_pk_bf16_f32 v1, v2, v3
	s_waitcnt lgkmcnt(4)
	v_cvt_pk_bf16_f32 v2, v6, v7
	s_waitcnt lgkmcnt(2)
	v_cvt_pk_bf16_f32 v3, v8, v9
	ds_read2_b32 v[6:7], v27 offset1:68
	ds_read2_b32 v[8:9], v27 offset0:136 offset1:204
	ds_read2_b32 v[10:11], v10 offset0:16 offset1:84
	v_lshl_add_u64 v[12:13], v[16:17], 1, v[4:5]
	global_store_dwordx4 v[12:13], v[0:3], off
	v_lshl_add_u64 v[4:5], v[18:19], 1, v[4:5]
	s_mov_b64 s[6:7], 0
	s_waitcnt lgkmcnt(2)
	v_cvt_pk_bf16_f32 v0, v6, v7
	s_waitcnt lgkmcnt(1)
	v_cvt_pk_bf16_f32 v1, v8, v9
	s_waitcnt lgkmcnt(0)
	v_cvt_pk_bf16_f32 v2, v10, v11
	v_cvt_pk_bf16_f32 v3, v14, v15
	global_store_dwordx4 v[4:5], v[0:3], off
	s_barrier
	s_mov_b32 s1, s44
	s_mov_b32 s2, s45
	s_nop 0
	s_lshr_b32 s1, s1, 16
	s_cmp_lg_u32 s1, 0
	s_cselect_b64 s[4:5], -1, 0
	s_cmp_lg_u64 s[4:5], 0
	s_addc_u32 s0, s2, s0
